# P0-SPLIT: 37% of the weight conversion (late FFN weights, units 1792-4095) moved from phase 0 into the idle workgroups of phases 1 and 3 (tail-round slack), on top of v062
# speedup vs baseline: 1.0085x; 1.0085x over previous
.LBB0_5:
	s_or_b64 exec, exec, s[0:1]
	s_add_u32 s24, s96, 0xea80000
	s_addc_u32 s25, s97, 0
	s_add_u32 s28, s96, 0x6080000
	s_addc_u32 s29, s97, 0
	s_add_u32 s20, s96, 0x8080000
	s_addc_u32 s35, s97, 0
	s_add_u32 s6, s96, 0x4200000
	s_addc_u32 s7, s97, 0
	v_writelane_b32 v250, s6, 50
	s_cmpk_lt_i32 s69, 0x200
	v_lshrrev_b32_e32 v1, 20, v0
	v_writelane_b32 v250, s7, 51
	s_cselect_b64 s[6:7], -1, 0
	v_writelane_b32 v250, s6, 52
	s_cmpk_eq_i32 s98, 0x100
	v_lshrrev_b32_e32 v0, 10, v0
	v_writelane_b32 v250, s7, 53
	s_cselect_b64 s[6:7], -1, 0
	v_writelane_b32 v250, s6, 54
	s_and_b32 s1, s69, 7
	s_lshr_b32 s86, s69, 3
	v_writelane_b32 v250, s7, 55
	s_ashr_i32 s6, s69, 3
	s_and_b32 s6, s6, -8
	s_or_b32 s87, s6, s1
	s_cmp_lg_u32 0, -1
	s_cselect_b64 s[30:31], -1, 0
	s_lshl_b32 s16, s69, 3
	s_lshl_b32 s83, s98, 3
	s_add_u32 s6, s96, 0x4e00000
	s_addc_u32 s7, s97, 0
	v_writelane_b32 v250, s6, 56
	s_ashr_i32 s1, s69, 31
	s_and_b32 s9, s29, 0xffff
	v_writelane_b32 v250, s7, 57
	v_writelane_b32 v250, s1, 58
	s_lshr_b32 s1, s1, 29
	s_add_i32 s1, s69, s1
	s_ashr_i32 s6, s1, 3
	s_and_b32 s1, s1, -8
	v_writelane_b32 v250, s6, 59
	s_sub_i32 s6, s69, s1
	s_ashr_i32 s1, s98, 31
	s_add_u32 s10, s96, 0xe280000
	v_writelane_b32 v250, s1, 60
	s_addc_u32 s11, s97, 0
	v_writelane_b32 v250, s10, 61
	s_mul_i32 s0, s99, s98
	v_or_b32_e32 v0, v0, v1
	v_writelane_b32 v250, s11, 62
	s_add_u32 s10, s96, 0xeb15100
	s_addc_u32 s11, s97, 0
	v_writelane_b32 v250, s10, 63
	s_mul_i32 s90, s0, s8
	v_readlane_b32 s36, v250, 2
	v_writelane_b32 v249, s11, 0
	s_add_u32 s10, s96, 0xeb11000
	s_addc_u32 s11, s97, 0
	s_not_b32 s1, s69
	v_writelane_b32 v249, s10, 1
	s_add_i32 s1, s98, s1
	s_cmp_lt_i32 s1, 64
	v_writelane_b32 v249, s11, 2
	v_writelane_b32 v249, s1, 3
	s_cselect_b64 s[10:11], -1, 0
	v_writelane_b32 v249, s10, 4
	s_movk_i32 s1, 0x3ff
	v_and_or_b32 v1, v0, s1, v220
	v_writelane_b32 v249, s11, 5
	s_add_u32 s10, s96, 0x4600000
	s_addc_u32 s11, s97, 0
	v_writelane_b32 v249, s10, 6
	v_readlane_b32 s46, v250, 12
	v_readlane_b32 s47, v250, 13
	v_writelane_b32 v249, s11, 7
	s_add_u32 s10, s96, 0xeb10000
	s_addc_u32 s11, s97, 0
	s_add_u32 s68, s96, 0xe680000
	s_addc_u32 s80, s97, 0
	s_lshl_b32 s91, s69, 9
	s_lshl_b32 s81, s98, 9
	v_writelane_b32 v249, s10, 8
	s_cmp_eq_u32 s69, 0
	s_cselect_b64 s[0:1], -1, 0
	v_writelane_b32 v249, s11, 9
	v_writelane_b32 v249, s0, 10
	s_cmpk_lt_i32 s69, 0x20a0
	s_mov_b32 s8, s28
	v_writelane_b32 v249, s1, 11
	s_cselect_b64 s[0:1], -1, 0
	v_writelane_b32 v249, s0, 12
	s_brev_b32 s10, 64
	v_cmp_eq_u32_e64 s[22:23], 0, v1
	v_writelane_b32 v249, s1, 13
	s_add_u32 s0, s96, 0xe080000
	s_addc_u32 s1, s97, 0
	s_add_u32 s70, s96, 0x5880000
	v_writelane_b32 v249, s0, 14
	s_addc_u32 s71, s97, 0
	s_mov_b32 s34, s20
	v_writelane_b32 v249, s1, 15
	s_add_u32 s0, s46, 0x1000
	s_addc_u32 s1, s47, 0
	v_writelane_b32 v249, s0, 16
	v_readlane_b32 s37, v250, 3
	s_mov_b32 s12, 0x41980000
	v_writelane_b32 v249, s1, 17
	s_add_u32 s0, s96, 0x5680000
	s_addc_u32 s1, s97, 0
	v_writelane_b32 v249, s0, 18
	s_mov_b32 s14, 0x41c80000
	v_mbcnt_lo_u32_b32 v227, -1, 0
	v_writelane_b32 v249, s1, 19
	s_add_u32 s0, s96, 0x5200000
	s_addc_u32 s1, s97, 0
	v_writelane_b32 v249, s0, 20
	v_mov_b32_e32 v0, 0
	s_mov_b32 s13, 0x41c00000
	v_writelane_b32 v249, s1, 21
	s_add_u32 s0, s96, 0x5e80000
	s_addc_u32 s1, s97, 0
	v_writelane_b32 v249, s0, 22
	s_mov_b32 s15, 0x41d00000
	v_mov_b32_e32 v221, 0x358637bd
	v_writelane_b32 v249, s1, 23
	s_add_u32 s0, s96, 0x3700000
	s_addc_u32 s1, s97, 0
	v_writelane_b32 v249, s0, 24
	v_mov_b32_e32 v222, 1
	v_mov_b32_e32 v223, 0x42800000
	v_writelane_b32 v249, s1, 25
	s_add_u32 s0, s96, 0x2100000
	s_addc_u32 s1, s97, 0
	v_writelane_b32 v249, s0, 26
	v_mov_b32_e32 v224, 0xfff
	v_mov_b32_e32 v225, 0x1800
	v_writelane_b32 v249, s1, 27
	s_add_u32 s0, s96, 0x1600000
	s_addc_u32 s1, s97, 0
	v_writelane_b32 v249, s0, 28
	s_cmp_eq_u64 s[96:97], 0
	v_mov_b32_e32 v226, 0xff800000
	v_writelane_b32 v249, s1, 29
	s_cselect_b64 s[0:1], -1, 0
	v_writelane_b32 v249, s0, 30
	v_mbcnt_hi_u32_b32 v228, -1, v227
	v_not_b32_e32 v229, 63
	v_writelane_b32 v249, s1, 31
	s_add_u32 s0, s96, 0xeb11300
	s_addc_u32 s1, s97, 0
	v_writelane_b32 v249, s0, 32
	v_mov_b32_e32 v230, 0xffffd0c0
	v_mov_b32_e32 v231, 0xffffd3c0
	v_writelane_b32 v249, s1, 33
	s_add_u32 s0, s96, 0xeb11500
	s_addc_u32 s1, s97, 0
	v_writelane_b32 v249, s0, 34
	v_mov_b32_e32 v232, 0xffffd4c0
	s_movk_i32 s89, 0x1800
	v_writelane_b32 v249, s1, 35
	s_add_u32 s0, s96, 0xeb11600
	s_addc_u32 s1, s97, 0
	v_writelane_b32 v249, s0, 36
	s_movk_i32 s19, 0x1200
	s_mov_b32 s17, 0
	v_writelane_b32 v249, s1, 37
	s_add_u32 s0, s96, 0xeb11700
	s_addc_u32 s1, s97, 0
	v_writelane_b32 v249, s0, 38
	s_mov_b32 s18, 0x3e38aa3b
	s_mov_b64 s[36:37], 0x80
	v_writelane_b32 v249, s1, 39
	s_add_u32 s0, s96, 0xeb11800
	s_addc_u32 s1, s97, 0
	v_writelane_b32 v249, s0, 40
	s_mov_b64 s[26:27], 0x400c0
	v_readlane_b32 s38, v250, 4
	v_writelane_b32 v249, s1, 41
	s_add_u32 s0, s96, 0xeb11900
	s_addc_u32 s1, s97, 0
	v_writelane_b32 v249, s0, 42
	v_readlane_b32 s39, v250, 5
	v_readlane_b32 s40, v250, 6
	v_writelane_b32 v249, s1, 43
	s_add_u32 s0, s96, 0xeb11a00
	s_addc_u32 s1, s97, 0
	v_writelane_b32 v249, s0, 44
	v_readlane_b32 s41, v250, 7
	v_readlane_b32 s42, v250, 8
	v_writelane_b32 v249, s1, 45
	s_add_u32 s0, s96, 0xeb11b00
	s_addc_u32 s1, s97, 0
	v_writelane_b32 v249, s0, 46
	v_readlane_b32 s43, v250, 9
	v_readlane_b32 s44, v250, 10
	v_writelane_b32 v249, s1, 47
	s_add_u32 s0, s96, 0xeb11c00
	s_addc_u32 s1, s97, 0
	v_writelane_b32 v249, s0, 48
	v_readlane_b32 s45, v250, 11
	v_readlane_b32 s48, v250, 14
	v_writelane_b32 v249, s1, 49
	s_add_u32 s0, s96, 0xeb11d00
	s_addc_u32 s1, s97, 0
	v_writelane_b32 v249, s0, 50
	v_readlane_b32 s49, v250, 15
	v_readlane_b32 s50, v250, 16
	v_writelane_b32 v249, s1, 51
	s_add_u32 s0, s96, 0xeb11e00
	s_addc_u32 s1, s97, 0
	v_writelane_b32 v249, s0, 52
	v_readlane_b32 s51, v250, 17
	s_nop 0
	v_writelane_b32 v249, s1, 53
	s_add_u32 s0, s96, 0xeb11f00
	s_addc_u32 s1, s97, 0
	v_writelane_b32 v249, s0, 54
	s_nop 1
	v_writelane_b32 v249, s1, 55
	s_add_u32 s0, s96, 0xeb12000
	s_addc_u32 s1, s97, 0
	v_writelane_b32 v249, s0, 56
	s_nop 1
	v_writelane_b32 v249, s1, 57
	s_add_u32 s0, s96, 0xeb12100
	s_addc_u32 s1, s97, 0
	v_writelane_b32 v249, s0, 58
	s_nop 1
	v_writelane_b32 v249, s1, 59
	s_add_u32 s0, s96, 0xeb12200
	s_addc_u32 s1, s97, 0
	v_writelane_b32 v249, s0, 60
	s_nop 1
	v_writelane_b32 v249, s1, 61
	s_add_u32 s0, s96, 0xeb12300
	s_addc_u32 s1, s97, 0
	v_writelane_b32 v249, s0, 62
	s_nop 1
	v_writelane_b32 v249, s1, 63
	s_add_u32 s0, s96, 0xeb12400
	s_addc_u32 s1, s97, 0
	v_writelane_b32 v248, s0, 0
	s_cmp_eq_u32 s3, 15
	s_nop 0
	v_writelane_b32 v248, s1, 1
	s_cselect_b64 s[0:1], -1, 0
	v_writelane_b32 v248, s0, 2
	s_cmp_eq_u32 s3, 14
	s_nop 0
	v_writelane_b32 v248, s1, 3
	s_cselect_b64 s[0:1], -1, 0
	v_writelane_b32 v248, s0, 4
	s_cmp_eq_u32 s3, 13
	s_nop 0
	v_writelane_b32 v248, s1, 5
	s_cselect_b64 s[0:1], -1, 0
	v_writelane_b32 v248, s0, 6
	s_cmp_eq_u32 s3, 12
	s_nop 0
	v_writelane_b32 v248, s1, 7
	s_cselect_b64 s[0:1], -1, 0
	v_writelane_b32 v248, s0, 8
	s_cmp_eq_u32 s3, 11
	s_nop 0
	v_writelane_b32 v248, s1, 9
	s_cselect_b64 s[0:1], -1, 0
	v_writelane_b32 v248, s0, 10
	s_cmp_eq_u32 s3, 10
	s_nop 0
	v_writelane_b32 v248, s1, 11
	s_cselect_b64 s[0:1], -1, 0
	v_writelane_b32 v248, s0, 12
	s_cmp_eq_u32 s3, 9
	s_nop 0
	v_writelane_b32 v248, s1, 13
	s_cselect_b64 s[0:1], -1, 0
	v_writelane_b32 v248, s0, 14
	s_cmp_eq_u32 s3, 8
	s_nop 0
	v_writelane_b32 v248, s1, 15
	s_cselect_b64 s[0:1], -1, 0
	v_writelane_b32 v248, s0, 16
	s_cmp_eq_u32 s3, 7
	s_nop 0
	v_writelane_b32 v248, s1, 17
	s_cselect_b64 s[0:1], -1, 0
	v_writelane_b32 v248, s0, 18
	s_cmp_eq_u32 s3, 6
	s_nop 0
	v_writelane_b32 v248, s1, 19
	s_cselect_b64 s[0:1], -1, 0
	v_writelane_b32 v248, s0, 20
	s_cmp_eq_u32 s3, 5
	s_nop 0
	v_writelane_b32 v248, s1, 21
	s_cselect_b64 s[0:1], -1, 0
	v_writelane_b32 v248, s0, 22
	s_cmp_eq_u32 s3, 4
	s_nop 0
	v_writelane_b32 v248, s1, 23
	s_cselect_b64 s[0:1], -1, 0
	v_writelane_b32 v248, s0, 24
	s_cmp_eq_u32 s3, 3
	s_nop 0
	v_writelane_b32 v248, s1, 25
	s_cselect_b64 s[0:1], -1, 0
	v_writelane_b32 v248, s0, 26
	s_cmp_eq_u32 s3, 2
	s_nop 0
	v_writelane_b32 v248, s1, 27
	s_cselect_b64 s[0:1], -1, 0
	v_writelane_b32 v248, s0, 28
	s_cmp_eq_u32 s3, 1
	s_nop 0
	v_writelane_b32 v248, s1, 29
	s_cselect_b64 s[0:1], -1, 0
	v_writelane_b32 v248, s0, 30
	s_cmp_eq_u32 s3, 0
	s_nop 0
	v_writelane_b32 v248, s1, 31
	s_cselect_b64 s[0:1], -1, 0
	v_writelane_b32 v248, s0, 32
	s_nop 1
	v_writelane_b32 v248, s1, 33
	s_lshl_b32 s0, s2, 2
	s_add_u32 s0, s4, s0
	s_addc_u32 s1, s5, 0
	s_add_u32 s2, s0, 0x1400
	s_addc_u32 s3, s1, 0
	v_writelane_b32 v248, s2, 34
	s_add_u32 s0, s0, 0x2400
	s_addc_u32 s1, s1, 0
	v_writelane_b32 v248, s3, 35
	v_writelane_b32 v248, s0, 36
	s_mov_b32 s3, 0x20000
	s_mov_b32 s11, s3
	v_writelane_b32 v248, s1, 37
	v_writelane_b32 v248, s8, 38
	s_add_u32 s0, s96, 0xeb14500
	s_addc_u32 s1, s97, 0
	v_writelane_b32 v248, s9, 39
	v_writelane_b32 v248, s10, 40
	v_writelane_b32 v248, s11, 41
	v_writelane_b32 v248, s0, 42
	s_brev_b32 s2, 32
	s_mov_b32 s4, 0x40400000
	v_writelane_b32 v248, s1, 43
	s_add_u32 s0, s96, 0xeb14600
	s_addc_u32 s1, s97, 0
	v_writelane_b32 v248, s0, 44
	s_mov_b32 s8, 0x41300000
	s_mov_b32 s10, 0x41880000
	v_writelane_b32 v248, s1, 45
	v_writelane_b32 v248, s6, 46
	s_lshr_b32 s0, s6, 31
	v_writelane_b32 v248, s0, 47
	s_lshl_b32 s0, s69, 6
	v_writelane_b32 v248, s0, 48
	s_lshl_b32 s0, s98, 6
	v_writelane_b32 v248, s0, 49
	s_add_u32 s0, s96, 0xe68c000
	v_writelane_b32 v248, s0, 50
	s_addc_u32 s0, s97, 0
	v_writelane_b32 v248, s0, 51
	s_add_u32 s0, s96, 0x8080020
	s_addc_u32 s1, s97, 0
	v_writelane_b32 v248, s0, 52
	s_lshl_b32 s82, s98, 1
	s_mov_b32 s6, 0x41100000
	v_writelane_b32 v248, s1, 53
	v_writelane_b32 v248, s0, 54
	s_mov_b32 s5, 0x41000000
	s_mov_b32 s7, 0x41200000
	v_writelane_b32 v248, s1, 55
	v_writelane_b32 v248, s2, 56
	v_writelane_b32 v248, s3, 57
	v_writelane_b32 v248, s16, 58
	s_add_i32 s0, s16, 0xfffeff00
	v_writelane_b32 v248, s0, 59
	s_lshl_b32 s0, s69, 1
	v_writelane_b32 v248, s0, 60
	s_add_i32 s0, 0, 0x240f0
	v_writelane_b32 v248, s0, 61
	s_add_i32 s0, 0, 0x240f4
	v_writelane_b32 v248, s0, 62
	v_writelane_b32 v248, s22, 63
	s_mov_b32 s9, 0x41800000
	s_mov_b32 s11, 0x41900000
	v_writelane_b32 v243, s23, 0
	v_writelane_b32 v243, s84, 1
	s_mov_b32 s3, 0xff800000
	s_add_i32 s33, 0, 0x12000
	v_writelane_b32 v243, s85, 2
	v_writelane_b32 v243, s28, 3
	s_mov_b32 s0, 0
	s_nop 0
	v_writelane_b32 v243, s29, 4
	v_writelane_b32 v243, s34, 5
	s_nop 1
	v_writelane_b32 v243, s35, 6
	v_writelane_b32 v243, s86, 7
	v_writelane_b32 v243, s87, 8
	v_writelane_b32 v243, s83, 9
	v_writelane_b32 v243, s68, 10
	v_writelane_b32 v243, s80, 11
	v_writelane_b32 v243, s90, 12
	v_writelane_b32 v243, s91, 13
	v_writelane_b32 v243, s81, 14
	v_writelane_b32 v243, s82, 15
	v_writelane_b32 v243, s69, 16
	v_writelane_b32 v243, s70, 17
	s_nop 1
	v_writelane_b32 v243, s71, 18
	v_writelane_b32 v243, 0, 60
	v_writelane_b32 v243, 0, 61
	s_branch .LBB0_9

.LBB0_282:
	s_or_b64 exec, exec, s[22:23]
	v_readlane_b32 s0, v249, 12
	v_readlane_b32 s1, v249, 13
	s_andn2_b64 vcc, exec, s[0:1]
	s_cbranch_vccnz .LBB0_391
	s_mov_b32 s100, s98
	s_movk_i32 s101, 0x209f
.Lp0_pre:
	v_lshlrev_b32_e32 v6, 4, v2
	v_and_b32_e32 v6, 48, v6
	v_ashrrev_i32_e32 v1, 8, v2
	s_movk_i32 s0, 0x4100
	v_lshlrev_b32_e32 v4, 2, v2
	s_waitcnt lgkmcnt(0)
	v_mul_u32_u24_e32 v11, 0x41, v6
	v_and_b32_e32 v5, 63, v2
	v_ashrrev_i32_e32 v7, 6, v2
	v_mad_i32_i24 v3, v1, s0, 0
	v_bfe_u32 v10, v2, 4, 4
	v_and_b32_e32 v4, 60, v4
	v_bfe_u32 v43, v2, 2, 6
	v_lshlrev_b32_e32 v11, 2, v11
	v_and_b32_e32 v2, 0xfc, v2
	v_readlane_b32 s40, v250, 2
	v_lshl_add_u32 v8, v4, 2, v3
	v_add3_u32 v44, v3, v11, v2
	v_add3_u32 v45, v3, v2, v11
	v_lshlrev_b32_e32 v2, 4, v5
	v_mov_b32_e32 v3, v0
	v_readlane_b32 s41, v250, 3
	v_readlane_b32 s42, v250, 4
	v_readlane_b32 s43, v250, 5
	v_readlane_b32 s0, v243, 3
	v_lshl_add_u64 v[14:15], s[40:41], 0, v[2:3]
	v_lshl_add_u64 v[12:13], s[42:43], 0, v[2:3]
	v_lshlrev_b32_e32 v2, 3, v5
	v_readlane_b32 s1, v243, 4
	v_mul_u32_u24_e32 v9, 0x104, v10
	v_cmp_eq_u32_e64 s[38:39], 0, v5
	v_lshl_add_u64 v[16:17], s[0:1], 0, v[2:3]
	v_readlane_b32 s0, v249, 14
	v_readlane_b32 s1, v249, 15
	v_or_b32_e32 v39, 16, v10
	v_or_b32_e32 v41, 32, v10
	v_lshl_add_u64 v[18:19], s[0:1], 0, v[2:3]
	v_readlane_b32 s0, v248, 59
	v_or_b32_e32 v42, 48, v10
	v_mov_b32_e32 v11, v0
	v_add_u32_e32 v20, s0, v7
	v_lshlrev_b32_e32 v22, 2, v4
	v_lshlrev_b32_e32 v24, 1, v6
	v_lshl_add_u32 v46, s69, 1, v1
	v_add_u32_e32 v47, v8, v9
	s_mov_b32 s2, s69
	s_mov_b32 s16, 0xb00000
	s_mov_b32 s21, 0x580000
	v_readlane_b32 s44, v250, 6
	v_readlane_b32 s45, v250, 7
	v_readlane_b32 s46, v250, 8
	v_readlane_b32 s47, v250, 9
	v_readlane_b32 s48, v250, 10
	v_readlane_b32 s49, v250, 11
	v_readlane_b32 s50, v250, 12
	v_readlane_b32 s51, v250, 13
	v_readlane_b32 s52, v250, 14
	v_readlane_b32 s53, v250, 15
	v_readlane_b32 s54, v250, 16
	v_readlane_b32 s55, v250, 17
	s_branch .LBB0_287

.LBB0_286:
	s_add_i32 s2, s2, s100
	v_add_u32_e32 v20, s83, v20
	v_add_u32_e32 v46, s82, v46
	s_cmpk_lg_u32 s100, 0x100
	s_cbranch_scc1 .Lp0_nohole
	s_cmpk_lt_i32 s2, 0x700
	s_cbranch_scc1 .Lp0_nohole
	s_cmpk_ge_i32 s2, 0x1000
	s_cbranch_scc1 .Lp0_nohole
	s_addk_i32 s2, 0x900
	v_add_u32_e32 v46, 0x1200, v46
	v_add_u32_e32 v20, 0x4800, v20
.Lp0_nohole:
	s_cmp_gt_i32 s2, s101
	s_cbranch_scc1 .LBB0_391

.LBB0_404:
	s_cmpk_lg_u32 s98, 0x100
	s_cbranch_scc1 .Lp0s_skip
	v_readlane_b32 s0, v243, 19
	v_readlane_b32 s1, v243, 61
	v_readlane_b32 s16, v243, 16
	s_cmp_eq_u32 s0, s1
	s_cbranch_scc1 .Lp0s_skip
	s_cmp_eq_u32 s0, 1
	s_cbranch_scc1 .Lp0s_ph1
	s_cmp_eq_u32 s0, 3
	s_cbranch_scc1 .Lp0s_ph3
	s_branch .Lp0s_skip
.Lp0s_ph1:
	s_cmpk_lt_u32 s16, 0x80
	s_cbranch_scc1 .Lp0s_skip
	s_cmpk_ge_u32 s16, 0xc0
	s_cbranch_scc1 .Lp0s_skip
	s_add_i32 s69, s16, 0x680
	s_movk_i32 s100, 0x40
	s_movk_i32 s101, 0x97f
	s_branch .Lp0s_go
.Lp0s_ph3:
	s_cmpk_lt_u32 s16, 0x40
	s_cbranch_scc1 .Lp0s_skip
	s_add_i32 s69, s16, 0x940
	s_movk_i32 s100, 0xc0
	s_movk_i32 s101, 0xfff
.Lp0s_go:
	v_writelane_b32 v243, s0, 61
	v_writelane_b32 v243, s2, 21
	v_writelane_b32 v243, s21, 22
	v_readlane_b32 s70, v243, 17
	v_readlane_b32 s71, v243, 18
	s_lshl_b32 s82, s100, 1
	s_lshl_b32 s83, s100, 3
	v_mov_b32_e32 v2, v220
	s_waitcnt vmcnt(0) lgkmcnt(0)
	s_barrier
	s_branch .Lp0_pre
.Lp0s_skip:
	v_readlane_b32 s82, v243, 15
	v_readlane_b32 s83, v243, 9
	v_readlane_b32 s69, v243, 16
	v_readlane_b32 s0, v243, 19
	v_readlane_b32 s22, v243, 20
	s_cmp_lg_u32 s0, 20
	s_mul_hi_u32 s16, s22, 0xcccccccd
	s_cselect_b64 s[0:1], -1, 0
	s_lshr_b32 s16, s16, 3
	s_mul_i32 s16, s16, 10
	s_sub_i32 s16, s22, s16
	s_cmp_lg_u32 s16, 6
	s_cselect_b64 s[22:23], -1, 0
	s_and_b64 s[0:1], s[0:1], s[22:23]
	s_andn2_b64 vcc, exec, s[0:1]
	s_cbranch_vccnz .LBB0_8
	s_waitcnt vmcnt(0)
	s_waitcnt vmcnt(0) lgkmcnt(0)
	s_barrier
	s_cmpk_lg_u32 s98, 0x100
	s_cbranch_scc1 .Ltb_cnt_done
	v_readlane_b32 s0, v243, 19
	s_mov_b32 s1, 0xc9f24
	s_lshr_b32 s1, s1, s0
	s_and_b32 s1, s1, 1
	s_cmp_eq_u32 s1, 0
	s_cbranch_scc1 .Ltb_cnt_done
	v_readlane_b32 s0, v243, 60
	s_add_i32 s0, s0, 1
	s_nop 0
	v_writelane_b32 v243, s0, 60
